# v90 + attention QK block: stale wait-state pads (guarding LDS reads that moved) and two dead VALU instructions removed
# baseline (speedup 1.0000x reference)
; #define LAS __attribute__((address_space(3)))
; __device__ __forceinline__ void attn_unit(const bf16* proj, unsigned char* ws, LAS unsigned char* lds, int a) {
;     ...
;         f32x4 st[2][8];
; #pragma unroll
;         for (int kt = 0; kt < 8; ++kt) { st[0][kt] = (f32x4){0.f, 0.f, 0.f, 0.f}; st[1][kt] = (f32x4){0.f, 0.f, 0.f, 0.f}; }
; #pragma unroll
;         for (int s = 0; s < 4; ++s) {
;             const bf16x8 qa = *(const LAS bf16x8*)(qbase + 64 * s), qb = *(const LAS bf16x8*)(qbase + 16 * QK_STRIDE + 64 * s);
; #pragma unroll
;             for (int kt = 0; kt < 8; ++kt) {
;                 const bf16x8 kf = *(const LAS bf16x8*)(KS + (16 * kt + fr) * QK_STRIDE + (32 * s + 8 * fq) * 2);
;                 st[0][kt] = __builtin_amdgcn_mfma_f32_16x16x32_bf16(kf, qa, st[0][kt], 0, 0, 0);
;                 st[1][kt] = __builtin_amdgcn_mfma_f32_16x16x32_bf16(kf, qb, st[1][kt], 0, 0, 0);
;             }
;         }
.LBB0_608:
	ds_read_b128 v[92:95], v205
	ds_read_b128 v[100:103], v205 offset:4352
	ds_read_b128 v[104:107], v201
	ds_read_b128 v[112:115], v201 offset:4352
	ds_read_b128 v[120:123], v201 offset:8704
	ds_read_b128 v[128:131], v201 offset:13056
	ds_read_b128 v[136:139], v201 offset:17408
	ds_read_b128 v[144:147], v201 offset:21760
	ds_read_b128 v[152:155], v201 offset:26112
	ds_read_b128 v[210:213], v201 offset:30464
	s_waitcnt lgkmcnt(7)
	v_mfma_f32_16x16x32_bf16 v[108:111], v[104:107], v[92:95], 0
	s_cmp_lg_u32 s72, s51
	s_cselect_b64 s[56:57], -1, 0
	s_cmp_lt_u32 s70, s69
	v_mfma_f32_16x16x32_bf16 v[104:107], v[104:107], v[100:103], 0
	s_cselect_b64 s[4:5], -1, 0
	s_waitcnt lgkmcnt(6)
	v_mfma_f32_16x16x32_bf16 v[116:119], v[112:115], v[92:95], 0
	s_cmp_eq_u32 s72, s51
	v_mfma_f32_16x16x32_bf16 v[112:115], v[112:115], v[100:103], 0
	s_waitcnt lgkmcnt(5)
	v_mfma_f32_16x16x32_bf16 v[124:127], v[120:123], v[92:95], 0
	v_mfma_f32_16x16x32_bf16 v[120:123], v[120:123], v[100:103], 0
	s_waitcnt lgkmcnt(4)
	v_mfma_f32_16x16x32_bf16 v[132:135], v[128:131], v[92:95], 0
	v_mfma_f32_16x16x32_bf16 v[128:131], v[128:131], v[100:103], 0
	s_waitcnt lgkmcnt(3)
	v_mfma_f32_16x16x32_bf16 v[140:143], v[136:139], v[92:95], 0
	v_mfma_f32_16x16x32_bf16 v[136:139], v[136:139], v[100:103], 0
	ds_read_b128 v[246:249], v201 offset:64
	s_waitcnt lgkmcnt(3)
	v_mfma_f32_16x16x32_bf16 v[148:151], v[144:147], v[92:95], 0
	v_mfma_f32_16x16x32_bf16 v[144:147], v[144:147], v[100:103], 0
	ds_read_b128 v[250:253], v201 offset:4416
	s_waitcnt lgkmcnt(3)
	v_mfma_f32_16x16x32_bf16 v[156:159], v[152:155], v[92:95], 0
	v_mfma_f32_16x16x32_bf16 v[152:155], v[152:155], v[100:103], 0
	ds_read_b128 v[218:221], v201 offset:8768
	s_waitcnt lgkmcnt(3)
	v_mfma_f32_16x16x32_bf16 v[92:95], v[210:213], v[92:95], 0
	v_mfma_f32_16x16x32_bf16 v[100:103], v[210:213], v[100:103], 0
	ds_read_b128 v[210:213], v205 offset:64
	ds_read_b128 v[214:217], v205 offset:4416
	ds_read_b128 v[238:241], v201 offset:13120
	s_waitcnt lgkmcnt(2)
	v_mfma_f32_16x16x32_bf16 v[108:111], v[246:249], v[210:213], v[108:111]
	s_waitcnt lgkmcnt(1)
	v_mfma_f32_16x16x32_bf16 v[104:107], v[246:249], v[214:217], v[104:107]
	ds_read_b128 v[246:249], v201 offset:17472
	v_mfma_f32_16x16x32_bf16 v[116:119], v[250:253], v[210:213], v[116:119]
	v_mfma_f32_16x16x32_bf16 v[112:115], v[250:253], v[214:217], v[112:115]
	ds_read_b128 v[250:253], v201 offset:21824
	v_mfma_f32_16x16x32_bf16 v[124:127], v[218:221], v[210:213], v[124:127]
	v_mfma_f32_16x16x32_bf16 v[120:123], v[218:221], v[214:217], v[120:123]
	ds_read_b128 v[218:221], v201 offset:26176
	s_waitcnt lgkmcnt(3)
	v_mfma_f32_16x16x32_bf16 v[132:135], v[238:241], v[210:213], v[132:135]
	v_mfma_f32_16x16x32_bf16 v[128:131], v[238:241], v[214:217], v[128:131]
	ds_read_b128 v[238:241], v201 offset:30528
	s_waitcnt lgkmcnt(3)
	v_mfma_f32_16x16x32_bf16 v[140:143], v[246:249], v[210:213], v[140:143]
	v_mfma_f32_16x16x32_bf16 v[136:139], v[246:249], v[214:217], v[136:139]
	ds_read_b128 v[246:249], v201 offset:128
	s_waitcnt lgkmcnt(3)
	v_mfma_f32_16x16x32_bf16 v[148:151], v[250:253], v[210:213], v[148:151]
	v_mfma_f32_16x16x32_bf16 v[144:147], v[250:253], v[214:217], v[144:147]
	ds_read_b128 v[250:253], v201 offset:4480
	s_waitcnt lgkmcnt(3)
	v_mfma_f32_16x16x32_bf16 v[156:159], v[218:221], v[210:213], v[156:159]
	v_mfma_f32_16x16x32_bf16 v[152:155], v[218:221], v[214:217], v[152:155]
	ds_read_b128 v[218:221], v201 offset:8832
	s_waitcnt lgkmcnt(3)
	v_mfma_f32_16x16x32_bf16 v[92:95], v[238:241], v[210:213], v[92:95]
	v_mfma_f32_16x16x32_bf16 v[100:103], v[238:241], v[214:217], v[100:103]
	ds_read_b128 v[210:213], v205 offset:128
	ds_read_b128 v[214:217], v205 offset:4480
	ds_read_b128 v[238:241], v201 offset:13184
	s_waitcnt lgkmcnt(2)
	v_mfma_f32_16x16x32_bf16 v[108:111], v[246:249], v[210:213], v[108:111]
	s_waitcnt lgkmcnt(1)
	v_mfma_f32_16x16x32_bf16 v[104:107], v[246:249], v[214:217], v[104:107]
	ds_read_b128 v[246:249], v201 offset:17536
	v_mfma_f32_16x16x32_bf16 v[116:119], v[250:253], v[210:213], v[116:119]
	v_mfma_f32_16x16x32_bf16 v[112:115], v[250:253], v[214:217], v[112:115]
	ds_read_b128 v[250:253], v201 offset:21888
	v_mfma_f32_16x16x32_bf16 v[124:127], v[218:221], v[210:213], v[124:127]
	v_mfma_f32_16x16x32_bf16 v[120:123], v[218:221], v[214:217], v[120:123]
	ds_read_b128 v[242:245], v201 offset:26240
	s_waitcnt lgkmcnt(3)
	v_mfma_f32_16x16x32_bf16 v[222:225], v[238:241], v[210:213], v[132:135]
	v_mfma_f32_16x16x32_bf16 v[128:131], v[238:241], v[214:217], v[128:131]
	s_waitcnt lgkmcnt(2)
	v_mfma_f32_16x16x32_bf16 v[218:221], v[246:249], v[210:213], v[140:143]
	v_mfma_f32_16x16x32_bf16 v[226:229], v[246:249], v[214:217], v[136:139]
	ds_read_b128 v[246:249], v201 offset:30592
	s_waitcnt lgkmcnt(2)
; #define LAS __attribute__((address_space(3)))
; __device__ __forceinline__ void attn_unit(const bf16* proj, unsigned char* ws, LAS unsigned char* lds, int a) {
;     ...
; #pragma unroll
;         for (int s = 0; s < 4; ++s) {
;             const bf16x8 qa = *(const LAS bf16x8*)(qbase + 64 * s), qb = *(const LAS bf16x8*)(qbase + 16 * QK_STRIDE + 64 * s);
; #pragma unroll
;             for (int kt = 0; kt < 8; ++kt) {
;                 const bf16x8 kf = *(const LAS bf16x8*)(KS + (16 * kt + fr) * QK_STRIDE + (32 * s + 8 * fq) * 2);
;                 st[0][kt] = __builtin_amdgcn_mfma_f32_16x16x32_bf16(kf, qa, st[0][kt], 0, 0, 0);
;                 st[1][kt] = __builtin_amdgcn_mfma_f32_16x16x32_bf16(kf, qb, st[1][kt], 0, 0, 0);
;             }
;         }
;         bf16x8 pb[2][4];
; #pragma unroll
;         for (int rt = 0; rt < 2; ++rt) {
;             const int qi = rq * 32 + rt * 16 + fr;
;             if (kb != n) {
;                 const int sgn = (kb < n) ? 1 : -1, dbase = sgn * (4 * fq - qi);
; #pragma unroll
;                 for (int kt = 0; kt < 8; ++kt)
; #pragma unroll
;                     for (int r = 0; r < 4; ++r) { const int dd = dbase + sgn * (16 * kt + r); st[rt][kt][r] += __builtin_bit_cast(float, (unsigned)(dd >> 31) & 0xF149F2CAu); }
;             }
;             float mx = -1e30f;
	v_mfma_f32_16x16x32_bf16 v[148:151], v[250:253], v[210:213], v[148:151]
	v_mfma_f32_16x16x32_bf16 v[230:233], v[250:253], v[214:217], v[144:147]
	ds_read_b128 v[250:253], v201 offset:192
	s_waitcnt lgkmcnt(2)
	v_mfma_f32_16x16x32_bf16 v[156:159], v[242:245], v[210:213], v[156:159]
	v_mfma_f32_16x16x32_bf16 v[234:237], v[242:245], v[214:217], v[152:155]
	s_waitcnt lgkmcnt(1)
	v_mfma_f32_16x16x32_bf16 v[214:217], v[246:249], v[214:217], v[100:103]
	ds_read_b128 v[238:241], v205 offset:192
	ds_read_b128 v[242:245], v205 offset:4544
	s_nop 0
	s_waitcnt lgkmcnt(0)
	v_mfma_f32_16x16x32_bf16 v[140:143], v[250:253], v[242:245], v[104:107]
	v_mfma_f32_16x16x32_bf16 v[210:213], v[246:249], v[210:213], v[92:95]
	ds_read_b128 v[246:249], v201 offset:4544
	v_mfma_f32_16x16x32_bf16 v[92:95], v[250:253], v[238:241], v[108:111]
	ds_read_b128 v[250:253], v201 offset:8896
	s_waitcnt lgkmcnt(1)
	v_mfma_f32_16x16x32_bf16 v[136:139], v[246:249], v[242:245], v[112:115]
	v_mfma_f32_16x16x32_bf16 v[100:103], v[246:249], v[238:241], v[116:119]
	ds_read_b128 v[246:249], v201 offset:13248
	s_waitcnt lgkmcnt(1)
	v_mfma_f32_16x16x32_bf16 v[104:107], v[250:253], v[238:241], v[124:127]
	v_mfma_f32_16x16x32_bf16 v[132:135], v[250:253], v[242:245], v[120:123]
	ds_read_b128 v[250:253], v201 offset:17600
	s_waitcnt lgkmcnt(1)
	v_mfma_f32_16x16x32_bf16 v[108:111], v[246:249], v[238:241], v[222:225]
	v_mfma_f32_16x16x32_bf16 v[128:131], v[246:249], v[242:245], v[128:131]
	ds_read_b128 v[246:249], v201 offset:21952
	s_waitcnt lgkmcnt(1)
	v_mfma_f32_16x16x32_bf16 v[144:147], v[250:253], v[238:241], v[218:221]
	v_mfma_f32_16x16x32_bf16 v[124:127], v[250:253], v[242:245], v[226:229]
	ds_read_b128 v[250:253], v201 offset:26304
	s_waitcnt lgkmcnt(1)
	v_mfma_f32_16x16x32_bf16 v[148:151], v[246:249], v[238:241], v[148:151]
	v_mfma_f32_16x16x32_bf16 v[120:123], v[246:249], v[242:245], v[230:233]
	ds_read_b128 v[246:249], v201 offset:30656
	s_waitcnt lgkmcnt(1)
	v_mfma_f32_16x16x32_bf16 v[152:155], v[250:253], v[238:241], v[156:159]
	v_mfma_f32_16x16x32_bf16 v[116:119], v[250:253], v[242:245], v[234:237]
	s_waitcnt lgkmcnt(0)
	v_mfma_f32_16x16x32_bf16 v[156:159], v[246:249], v[238:241], v[210:213]
	v_mfma_f32_16x16x32_bf16 v[112:115], v[246:249], v[242:245], v[214:217]
	s_nop 3
	s_cbranch_scc1 .LBB0_610
	s_cmp_lt_u32 s70, s69
	s_cbranch_scc0 .Lam_a_next
	v_cmp_gt_i32_e32 vcc, 0, v181
	v_cndmask_b32_e32 v92, v92, v171, vcc
	v_cmp_gt_i32_e32 vcc, -1, v181
	v_cndmask_b32_e32 v93, v93, v171, vcc
	v_cmp_gt_i32_e32 vcc, -2, v181
	v_cndmask_b32_e32 v94, v94, v171, vcc
	v_cmp_gt_i32_e32 vcc, -3, v181
	v_cndmask_b32_e32 v95, v95, v171, vcc
	v_cmp_gt_i32_e32 vcc, -16, v181
	v_cndmask_b32_e32 v100, v100, v171, vcc
	v_cmp_gt_i32_e32 vcc, 0xffffffef, v181
	v_cndmask_b32_e32 v101, v101, v171, vcc
	v_cmp_gt_i32_e32 vcc, 0xffffffee, v181
	v_cndmask_b32_e32 v102, v102, v171, vcc
	v_cmp_gt_i32_e32 vcc, 0xffffffed, v181
	v_cndmask_b32_e32 v103, v103, v171, vcc
	v_cmp_gt_i32_e32 vcc, 0xffffffe0, v181
	v_cndmask_b32_e32 v104, v104, v171, vcc
	v_cmp_gt_i32_e32 vcc, 0xffffffdf, v181
	v_cndmask_b32_e32 v105, v105, v171, vcc
	v_cmp_gt_i32_e32 vcc, 0xffffffde, v181
	v_cndmask_b32_e32 v106, v106, v171, vcc
	v_cmp_gt_i32_e32 vcc, 0xffffffdd, v181
	v_cndmask_b32_e32 v107, v107, v171, vcc
	v_cmp_gt_i32_e32 vcc, 0xffffffd0, v181
	v_cndmask_b32_e32 v108, v108, v171, vcc
	v_cmp_gt_i32_e32 vcc, 0xffffffcf, v181
	v_cndmask_b32_e32 v109, v109, v171, vcc
	v_cmp_gt_i32_e32 vcc, 0xffffffce, v181
	v_cndmask_b32_e32 v110, v110, v171, vcc
	v_cmp_gt_i32_e32 vcc, 0xffffffcd, v181
	v_cndmask_b32_e32 v111, v111, v171, vcc
	v_cmp_gt_i32_e32 vcc, 0xffffffc0, v181
	v_cndmask_b32_e32 v144, v144, v171, vcc
	v_cmp_gt_i32_e32 vcc, 0xffffffbf, v181
	v_cndmask_b32_e32 v145, v145, v171, vcc
	v_cmp_gt_i32_e32 vcc, 0xffffffbe, v181
	v_cndmask_b32_e32 v146, v146, v171, vcc
	v_cmp_gt_i32_e32 vcc, 0xffffffbd, v181
	v_cndmask_b32_e32 v147, v147, v171, vcc
	v_cmp_gt_i32_e32 vcc, 0xffffffb0, v181
	v_cndmask_b32_e32 v148, v148, v171, vcc
	v_cmp_gt_i32_e32 vcc, 0xffffffaf, v181
	v_cndmask_b32_e32 v149, v149, v171, vcc
	v_cmp_gt_i32_e32 vcc, 0xffffffae, v181
	v_cndmask_b32_e32 v150, v150, v171, vcc
	v_cmp_gt_i32_e32 vcc, 0xffffffad, v181
	v_cndmask_b32_e32 v151, v151, v171, vcc
	v_cmp_gt_i32_e32 vcc, 0xffffffa0, v181
	v_cndmask_b32_e32 v152, v152, v171, vcc
	v_cmp_gt_i32_e32 vcc, 0xffffff9f, v181
	v_cndmask_b32_e32 v153, v153, v171, vcc
	v_cmp_gt_i32_e32 vcc, 0xffffff9e, v181
	v_cndmask_b32_e32 v154, v154, v171, vcc
	v_cmp_gt_i32_e32 vcc, 0xffffff9d, v181
	v_cndmask_b32_e32 v155, v155, v171, vcc
	v_cmp_gt_i32_e32 vcc, 0xffffff90, v181
	v_cndmask_b32_e32 v156, v156, v171, vcc
	v_cmp_gt_i32_e32 vcc, 0xffffff8f, v181
	v_cndmask_b32_e32 v157, v157, v171, vcc
	v_cmp_gt_i32_e32 vcc, 0xffffff8e, v181
	v_cndmask_b32_e32 v158, v158, v171, vcc
	v_cmp_gt_i32_e32 vcc, 0xffffff8d, v181
	v_cndmask_b32_e32 v159, v159, v171, vcc
	s_branch .LBB0_610
